# phase_gates Ws staging: 8 loads in flight with counted waits instead of an 8-iteration load/vmcnt(0)/ds_write loop
# speedup vs baseline: 1.0053x; 1.0053x over previous
; #define LAS __attribute__((address_space(3)))
; DI void phase_gates(const Params& p, LAS unsigned char* lds, const bf16* H, int tid, int lane, int wave, int bidx, int nblk) {
;     ...
;     __syncthreads();
;     for (int i = tid; i < 32 * 128; i += 512) { const int rw = i >> 7, c = i & 127; *(LAS u32x4*)(Ws + rw * GP + c * 8) = *(const u32x4*)(WG + rw * 1024 + c * 8); }
;     __syncthreads();
.LBB0_157:
	s_movk_i32 s0, 0x1000
	v_cmp_gt_i32_e32 vcc, s0, v144
	s_waitcnt vmcnt(0)
	s_barrier
	s_and_saveexec_b64 s[0:1], vcc
	s_cbranch_execz .LBB0_160
	v_ashrrev_i32_e32 v8, 7, v144
	v_lshlrev_b32_e32 v0, 4, v144
	v_and_b32_e32 v0, 0x7f0, v0
	v_lshl_add_u32 v2, v8, 11, v0
	s_movk_i32 s2, 0x810
	v_mul_lo_u32 v8, v8, s2
	v_add_u32_e32 v0, v8, v0
	global_load_dwordx4 v[48:51], v2, s[36:37]
	v_add_u32_e32 v2, 0x2000, v2
	global_load_dwordx4 v[52:55], v2, s[36:37]
	v_add_u32_e32 v2, 0x2000, v2
	global_load_dwordx4 v[56:59], v2, s[36:37]
	v_add_u32_e32 v2, 0x2000, v2
	global_load_dwordx4 v[60:63], v2, s[36:37]
	v_add_u32_e32 v2, 0x2000, v2
	global_load_dwordx4 v[64:67], v2, s[36:37]
	v_add_u32_e32 v2, 0x2000, v2
	global_load_dwordx4 v[68:71], v2, s[36:37]
	v_add_u32_e32 v2, 0x2000, v2
	global_load_dwordx4 v[72:75], v2, s[36:37]
	v_add_u32_e32 v2, 0x2000, v2
	global_load_dwordx4 v[76:79], v2, s[36:37]
	s_waitcnt vmcnt(7)
	ds_write_b128 v0, v[48:51]
	s_waitcnt vmcnt(6)
	ds_write_b128 v0, v[52:55] offset:8256
	s_waitcnt vmcnt(5)
	ds_write_b128 v0, v[56:59] offset:16512
	s_waitcnt vmcnt(4)
	ds_write_b128 v0, v[60:63] offset:24768
	s_waitcnt vmcnt(3)
	ds_write_b128 v0, v[64:67] offset:33024
	s_waitcnt vmcnt(2)
	ds_write_b128 v0, v[68:71] offset:41280
	s_waitcnt vmcnt(1)
	ds_write_b128 v0, v[72:75] offset:49536
	s_waitcnt vmcnt(0)
	ds_write_b128 v0, v[76:79] offset:57792
	s_nop 0
	s_nop 0
